# SSD chunk: six scale-vector reads hoisted (on top of v41)
# baseline (speedup 1.0000x reference)
.LBB0_658:
	s_andn2_saveexec_b64 s[48:49], s[48:49]
	s_cbranch_execz .LBB0_660
	v_cvt_pk_bf16_f32 v198, v136, s0
	ds_write_b16 v183, v198 offset:8576
	v_cvt_pk_bf16_f32 v198, v137, s0
	ds_write_b16 v183, v198 offset:8848
	v_cvt_pk_bf16_f32 v198, v134, s0
	ds_write_b16 v183, v198 offset:9120
	v_cvt_pk_bf16_f32 v198, v135, s0
	ds_write_b16 v183, v198 offset:9392
	v_cvt_pk_bf16_f32 v198, v132, s0
	ds_write_b16 v183, v198 offset:9664
	v_cvt_pk_bf16_f32 v198, v133, s0
	ds_write_b16 v183, v198 offset:9936
	v_cvt_pk_bf16_f32 v198, v130, s0
	ds_write_b16 v183, v198 offset:10208
	v_cvt_pk_bf16_f32 v198, v131, s0
	ds_write_b16 v183, v198 offset:10480
	v_cvt_pk_bf16_f32 v198, v144, s0
	ds_write_b16 v183, v198 offset:10752
	v_cvt_pk_bf16_f32 v198, v145, s0
	ds_write_b16 v183, v198 offset:11024
	v_cvt_pk_bf16_f32 v198, v142, s0
	ds_write_b16 v183, v198 offset:11296
	v_cvt_pk_bf16_f32 v198, v143, s0
	ds_write_b16 v183, v198 offset:11568
	v_cvt_pk_bf16_f32 v198, v140, s0
	ds_write_b16 v183, v198 offset:11840
	v_cvt_pk_bf16_f32 v198, v141, s0
	ds_write_b16 v183, v198 offset:12112
	v_cvt_pk_bf16_f32 v198, v138, s0
	ds_write_b16 v183, v198 offset:12384
	v_cvt_pk_bf16_f32 v198, v139, s0
	ds_write_b16 v183, v198 offset:12656
	v_cvt_pk_bf16_f32 v198, v152, s0
	ds_write_b16 v183, v198 offset:12928
	v_cvt_pk_bf16_f32 v198, v153, s0
	ds_write_b16 v183, v198 offset:13200
	v_cvt_pk_bf16_f32 v198, v150, s0
	ds_write_b16 v183, v198 offset:13472
	v_cvt_pk_bf16_f32 v198, v151, s0
	ds_write_b16 v183, v198 offset:13744
	v_cvt_pk_bf16_f32 v198, v148, s0
	ds_write_b16 v183, v198 offset:14016
	v_cvt_pk_bf16_f32 v198, v149, s0
	ds_write_b16 v183, v198 offset:14288
	v_cvt_pk_bf16_f32 v198, v146, s0
	ds_write_b16 v183, v198 offset:14560
	v_cvt_pk_bf16_f32 v198, v147, s0
	ds_write_b16 v183, v198 offset:14832
	v_cvt_pk_bf16_f32 v198, v160, s0
	ds_write_b16 v183, v198 offset:15104
	v_cvt_pk_bf16_f32 v198, v161, s0
	ds_write_b16 v183, v198 offset:15376
	v_cvt_pk_bf16_f32 v198, v158, s0
	ds_write_b16 v183, v198 offset:15648
	v_cvt_pk_bf16_f32 v198, v159, s0
	ds_write_b16 v183, v198 offset:15920
	v_cvt_pk_bf16_f32 v198, v156, s0
	ds_write_b16 v183, v198 offset:16192
	v_cvt_pk_bf16_f32 v198, v157, s0
	v_mul_lo_u32 v202, v179, s54
	ds_write_b16 v183, v198 offset:16464
	v_cvt_pk_bf16_f32 v198, v154, s0
	v_cvt_pk_bf16_f32 v203, v155, s0
	ds_write_b16 v183, v198 offset:16736
	ds_read_b128 v[198:201], v163 offset:53120
	ds_write_b16 v183, v203 offset:17008
	v_add_u32_e32 v183, 16, v202
	ds_read_b128 v[202:205], v163 offset:53136
	ds_read_b128 v[208:211], v163 offset:53152
	ds_read_b128 v[212:215], v163 offset:53168
	ds_read_b128 v[216:219], v163 offset:53184
	ds_read_b128 v[220:223], v163 offset:53200
	ds_read_b128 v[224:227], v163 offset:53216
	ds_read_b128 v[228:231], v163 offset:53232
	s_waitcnt lgkmcnt(8)
	v_pk_mul_f32 v[136:137], v[136:137], v[198:199]
	v_pk_mul_f32 v[134:135], v[134:135], v[200:201]
	v_cvt_pk_bf16_f32 v198, v136, v137
	s_waitcnt lgkmcnt(6)
	v_pk_mul_f32 v[132:133], v[132:133], v[202:203]
	v_pk_mul_f32 v[130:131], v[130:131], v[204:205]
	v_cvt_pk_bf16_f32 v199, v134, v135
	v_cvt_pk_bf16_f32 v200, v132, v133
	v_cvt_pk_bf16_f32 v201, v130, v131
	ds_write_b128 v183, v[198:201] offset:12288
	s_nop 0
	s_nop 0
	s_waitcnt lgkmcnt(6)
	v_pk_mul_f32 v[130:131], v[144:145], v[208:209]
	v_pk_mul_f32 v[132:133], v[142:143], v[210:211]
	v_cvt_pk_bf16_f32 v130, v130, v131
	v_cvt_pk_bf16_f32 v131, v132, v133
	s_waitcnt lgkmcnt(5)
	v_pk_mul_f32 v[132:133], v[140:141], v[212:213]
	v_pk_mul_f32 v[134:135], v[138:139], v[214:215]
	v_cvt_pk_bf16_f32 v132, v132, v133
	v_cvt_pk_bf16_f32 v133, v134, v135
	ds_write_b128 v183, v[130:133] offset:12304
	s_nop 0
	s_nop 0
	s_waitcnt lgkmcnt(5)
	v_pk_mul_f32 v[130:131], v[152:153], v[216:217]
	v_pk_mul_f32 v[132:133], v[150:151], v[218:219]
	v_cvt_pk_bf16_f32 v130, v130, v131
	v_cvt_pk_bf16_f32 v131, v132, v133
	s_waitcnt lgkmcnt(4)
	v_pk_mul_f32 v[132:133], v[148:149], v[220:221]
	v_pk_mul_f32 v[134:135], v[146:147], v[222:223]
	v_cvt_pk_bf16_f32 v132, v132, v133
	v_cvt_pk_bf16_f32 v133, v134, v135
	ds_write_b128 v183, v[130:133] offset:12320
	s_nop 0
	s_nop 0
	s_waitcnt lgkmcnt(4)
	v_pk_mul_f32 v[130:131], v[160:161], v[224:225]
	v_pk_mul_f32 v[132:133], v[158:159], v[226:227]
	v_cvt_pk_bf16_f32 v130, v130, v131
	v_cvt_pk_bf16_f32 v131, v132, v133
	s_waitcnt lgkmcnt(3)
	v_pk_mul_f32 v[132:133], v[156:157], v[228:229]
	v_pk_mul_f32 v[134:135], v[154:155], v[230:231]
	v_cvt_pk_bf16_f32 v132, v132, v133
	v_cvt_pk_bf16_f32 v133, v134, v135
	ds_write_b128 v183, v[130:133] offset:12336
